# out-proj K-loop also peeled (SrcC=0, relaxed first waits) on top of in-proj peel + LDS row statistics + pipelined residual epilogue
# baseline (speedup 1.0000x reference)
.LBB0_481:
	s_add_u32 s42, s44, 0x80
	s_addc_u32 s43, s45, 0
	s_add_u32 s44, s0, 0x100
	s_addc_u32 s45, s1, 0
	s_mov_b32 s0, 0
	s_add_i32 s47, s0, 2
	s_add_u32 s14, s42, 0x80
	s_addc_u32 s1, s43, 0
	s_add_i32 s15, 0, 0x10000
	s_cmp_eq_u32 s29, s0
	s_cselect_b32 s1, s77, s1
	s_cselect_b32 s0, s76, s14
	v_add_u32_e32 v150, s15, v165
	s_cselect_b32 s83, s79, s45
	s_cselect_b32 s82, s78, s44
	s_add_i32 s14, 0, 0x14000
	ds_read_b128 v[128:131], v150
	ds_read_b128 v[132:135], v150 offset:1024
	ds_read_b128 v[146:149], v150 offset:2048
	ds_read_b128 v[158:161], v150 offset:3072
	v_add_u32_e32 v150, s14, v165
	ds_read_b128 v[168:171], v150
	ds_read_b128 v[172:175], v150 offset:1024
	ds_read_b128 v[176:179], v150 offset:2048
	ds_read_b128 v[194:197], v150 offset:3072
	v_lshl_add_u64 v[150:151], s[42:43], 0, v[142:143]
	s_add_i32 m0, s3, 0xc000
	ds_read_b128 v[202:205], v167
	ds_read_b128 v[206:209], v167 offset:1024
	ds_read_b128 v[210:213], v167 offset:2048
	ds_read_b128 v[214:217], v167 offset:3072
	ds_read_b128 v[218:221], v167 offset:4096
	ds_read_b128 v[222:225], v167 offset:5120
	ds_read_b128 v[226:229], v167 offset:6144
	ds_read_b128 v[230:233], v167 offset:7168
	global_load_lds_dwordx4 v[150:151], off
	v_lshl_add_u64 v[150:151], s[42:43], 0, v[144:145]
	s_add_i32 m0, s3, 0xe000
	s_nop 0
	global_load_lds_dwordx4 v[150:151], off
	s_cmp_eq_u32 s92, 1
	s_cbranch_scc1 .Lpeel_strict482_1
	s_waitcnt vmcnt(24)
	s_branch .Lpeel_join482_1

.Lpeel_join482_1:
	s_waitcnt lgkmcnt(0)
	s_barrier
	s_setprio 1
	s_waitcnt lgkmcnt(0)
	v_mfma_f32_16x16x32_bf16 v[124:127], v[128:131], v[202:205], 0
	v_mfma_f32_16x16x32_bf16 v[120:123], v[146:149], v[202:205], 0
	v_mfma_f32_16x16x32_bf16 v[108:111], v[128:131], v[210:213], 0
	v_mfma_f32_16x16x32_bf16 v[104:107], v[146:149], v[210:213], 0
	v_mfma_f32_16x16x32_bf16 v[92:95], v[128:131], v[218:221], 0
	v_mfma_f32_16x16x32_bf16 v[88:91], v[146:149], v[218:221], 0
	v_mfma_f32_16x16x32_bf16 v[76:79], v[128:131], v[226:229], 0
	v_mfma_f32_16x16x32_bf16 v[72:75], v[146:149], v[226:229], 0
	v_mfma_f32_16x16x32_bf16 v[124:127], v[132:135], v[206:209], v[124:127]
	v_mfma_f32_16x16x32_bf16 v[120:123], v[158:161], v[206:209], v[120:123]
	v_mfma_f32_16x16x32_bf16 v[108:111], v[132:135], v[214:217], v[108:111]
	v_mfma_f32_16x16x32_bf16 v[104:107], v[158:161], v[214:217], v[104:107]
	v_mfma_f32_16x16x32_bf16 v[92:95], v[132:135], v[222:225], v[92:95]
	v_mfma_f32_16x16x32_bf16 v[88:91], v[158:161], v[222:225], v[88:91]
	v_mfma_f32_16x16x32_bf16 v[76:79], v[132:135], v[230:233], v[76:79]
	v_mfma_f32_16x16x32_bf16 v[72:75], v[158:161], v[230:233], v[72:75]
	s_setprio 0
	s_setprio 1
	v_mfma_f32_16x16x32_bf16 v[116:119], v[168:171], v[202:205], 0
	v_mfma_f32_16x16x32_bf16 v[112:115], v[176:179], v[202:205], 0
	v_mfma_f32_16x16x32_bf16 v[100:103], v[168:171], v[210:213], 0
	v_mfma_f32_16x16x32_bf16 v[96:99], v[176:179], v[210:213], 0
	v_mfma_f32_16x16x32_bf16 v[84:87], v[168:171], v[218:221], 0
	v_mfma_f32_16x16x32_bf16 v[80:83], v[176:179], v[218:221], 0
	v_mfma_f32_16x16x32_bf16 v[68:71], v[168:171], v[226:229], 0
	v_mfma_f32_16x16x32_bf16 v[64:67], v[176:179], v[226:229], 0
	v_mfma_f32_16x16x32_bf16 v[116:119], v[172:175], v[206:209], v[116:119]
	v_mfma_f32_16x16x32_bf16 v[112:115], v[194:197], v[206:209], v[112:115]
	v_mfma_f32_16x16x32_bf16 v[100:103], v[172:175], v[214:217], v[100:103]
	v_mfma_f32_16x16x32_bf16 v[96:99], v[194:197], v[214:217], v[96:99]
	v_mfma_f32_16x16x32_bf16 v[84:87], v[172:175], v[222:225], v[84:87]
	v_mfma_f32_16x16x32_bf16 v[80:83], v[194:197], v[222:225], v[80:83]
	v_mfma_f32_16x16x32_bf16 v[68:71], v[172:175], v[230:233], v[68:71]
	v_mfma_f32_16x16x32_bf16 v[64:67], v[194:197], v[230:233], v[64:67]
	s_setprio 0
	s_barrier
	s_add_i32 s15, s15, s2
	v_lshl_add_u64 v[150:151], s[82:83], 0, v[154:155]
	s_mov_b32 m0, s15
	ds_read_b128 v[202:205], v167 offset:16384
	ds_read_b128 v[206:209], v167 offset:17408
	ds_read_b128 v[210:213], v167 offset:18432
	ds_read_b128 v[214:217], v167 offset:19456
	ds_read_b128 v[218:221], v167 offset:20480
	ds_read_b128 v[222:225], v167 offset:21504
	ds_read_b128 v[226:229], v167 offset:22528
	ds_read_b128 v[230:233], v167 offset:23552
	global_load_lds_dwordx4 v[150:151], off
	s_add_i32 m0, s15, 0x2000
	v_lshl_add_u64 v[162:163], s[82:83], 0, v[140:141]
	s_add_u32 s82, s82, s24
	s_addc_u32 s83, s83, s25
	s_add_i32 s14, s14, s2
	global_load_lds_dwordx4 v[162:163], off
	v_lshl_add_u64 v[180:181], s[82:83], 0, v[154:155]
	s_mov_b32 m0, s14
	v_lshl_add_u64 v[234:235], s[82:83], 0, v[140:141]
	global_load_lds_dwordx4 v[180:181], off
	s_add_i32 m0, s14, 0x2000
	v_lshl_add_u64 v[236:237], s[0:1], 0, v[136:137]
	global_load_lds_dwordx4 v[234:235], off
	s_mov_b32 m0, s3
	v_lshl_add_u64 v[238:239], s[0:1], 0, v[138:139]
	global_load_lds_dwordx4 v[236:237], off
	s_mov_b32 m0, s10
	s_nop 0
	global_load_lds_dwordx4 v[238:239], off
	s_cmp_eq_u32 s92, 1
	s_cbranch_scc1 .Lpeel_strict482_2
	s_waitcnt vmcnt(24)
	s_branch .Lpeel_join482_2

.Lpeel_join482_2:
	s_waitcnt lgkmcnt(0)
	s_barrier
	s_setprio 1
	s_waitcnt lgkmcnt(0)
	v_mfma_f32_16x16x32_bf16 v[60:63], v[128:131], v[202:205], 0
	v_mfma_f32_16x16x32_bf16 v[56:59], v[146:149], v[202:205], 0
	v_mfma_f32_16x16x32_bf16 v[44:47], v[128:131], v[210:213], 0
	v_mfma_f32_16x16x32_bf16 v[40:43], v[146:149], v[210:213], 0
	v_mfma_f32_16x16x32_bf16 v[28:31], v[128:131], v[218:221], 0
	v_mfma_f32_16x16x32_bf16 v[24:27], v[146:149], v[218:221], 0
	v_mfma_f32_16x16x32_bf16 v[12:15], v[128:131], v[226:229], 0
	v_mfma_f32_16x16x32_bf16 v[8:11], v[146:149], v[226:229], 0
	v_mfma_f32_16x16x32_bf16 v[60:63], v[132:135], v[206:209], v[60:63]
	v_mfma_f32_16x16x32_bf16 v[56:59], v[158:161], v[206:209], v[56:59]
	v_mfma_f32_16x16x32_bf16 v[44:47], v[132:135], v[214:217], v[44:47]
	v_mfma_f32_16x16x32_bf16 v[40:43], v[158:161], v[214:217], v[40:43]
	v_mfma_f32_16x16x32_bf16 v[28:31], v[132:135], v[222:225], v[28:31]
	v_mfma_f32_16x16x32_bf16 v[24:27], v[158:161], v[222:225], v[24:27]
	v_mfma_f32_16x16x32_bf16 v[12:15], v[132:135], v[230:233], v[12:15]
	v_mfma_f32_16x16x32_bf16 v[8:11], v[158:161], v[230:233], v[8:11]
	s_setprio 0
	s_setprio 1
	v_mfma_f32_16x16x32_bf16 v[52:55], v[168:171], v[202:205], 0
	v_mfma_f32_16x16x32_bf16 v[48:51], v[176:179], v[202:205], 0
	v_mfma_f32_16x16x32_bf16 v[36:39], v[168:171], v[210:213], 0
	v_mfma_f32_16x16x32_bf16 v[32:35], v[176:179], v[210:213], 0
	v_mfma_f32_16x16x32_bf16 v[20:23], v[168:171], v[218:221], 0
	v_mfma_f32_16x16x32_bf16 v[16:19], v[176:179], v[218:221], 0
	v_mfma_f32_16x16x32_bf16 v[4:7], v[168:171], v[226:229], 0
	v_mfma_f32_16x16x32_bf16 v[0:3], v[176:179], v[226:229], 0
	v_mfma_f32_16x16x32_bf16 v[52:55], v[172:175], v[206:209], v[52:55]
	v_mfma_f32_16x16x32_bf16 v[48:51], v[194:197], v[206:209], v[48:51]
	v_mfma_f32_16x16x32_bf16 v[36:39], v[172:175], v[214:217], v[36:39]
	v_mfma_f32_16x16x32_bf16 v[32:35], v[194:197], v[214:217], v[32:35]
	v_mfma_f32_16x16x32_bf16 v[20:23], v[172:175], v[222:225], v[20:23]
	v_mfma_f32_16x16x32_bf16 v[16:19], v[194:197], v[222:225], v[16:19]
	v_mfma_f32_16x16x32_bf16 v[4:7], v[172:175], v[230:233], v[4:7]
	v_mfma_f32_16x16x32_bf16 v[0:3], v[194:197], v[230:233], v[0:3]
	s_setprio 0
	s_barrier
	s_add_i32 s14, 0, 0x18000
	s_add_i32 s15, 0, 0x1c000
	v_add_u32_e32 v158, s14, v165
	v_add_u32_e32 v193, s15, v165
	ds_read_b128 v[128:131], v158
	ds_read_b128 v[132:135], v158 offset:1024
	ds_read_b128 v[146:149], v158 offset:2048
	ds_read_b128 v[158:161], v158 offset:3072
	ds_read_b128 v[168:171], v193
	ds_read_b128 v[172:175], v193 offset:1024
	ds_read_b128 v[176:179], v193 offset:2048
	ds_read_b128 v[194:197], v193 offset:3072
	s_add_u32 s0, s0, s8
	s_addc_u32 s1, s1, s9
	s_mov_b32 m0, s11
	v_lshl_add_u64 v[240:241], s[0:1], 0, v[136:137]
	ds_read_b128 v[202:205], v167 offset:32768
	ds_read_b128 v[206:209], v167 offset:33792
	ds_read_b128 v[210:213], v167 offset:34816
	ds_read_b128 v[214:217], v167 offset:35840
	ds_read_b128 v[218:221], v167 offset:36864
	ds_read_b128 v[222:225], v167 offset:37888
	ds_read_b128 v[226:229], v167 offset:38912
	ds_read_b128 v[230:233], v167 offset:39936
	global_load_lds_dwordx4 v[240:241], off
	v_lshl_add_u64 v[240:241], s[0:1], 0, v[138:139]
	s_mov_b32 m0, s13
	s_nop 0
	global_load_lds_dwordx4 v[240:241], off
	s_waitcnt vmcnt(8)
	s_waitcnt lgkmcnt(0)
	s_barrier
	s_setprio 1
	s_waitcnt lgkmcnt(0)
	v_mfma_f32_16x16x32_bf16 v[124:127], v[128:131], v[202:205], v[124:127]
	v_mfma_f32_16x16x32_bf16 v[120:123], v[146:149], v[202:205], v[120:123]
	v_mfma_f32_16x16x32_bf16 v[108:111], v[128:131], v[210:213], v[108:111]
	v_mfma_f32_16x16x32_bf16 v[104:107], v[146:149], v[210:213], v[104:107]
	v_mfma_f32_16x16x32_bf16 v[92:95], v[128:131], v[218:221], v[92:95]
	v_mfma_f32_16x16x32_bf16 v[88:91], v[146:149], v[218:221], v[88:91]
	v_mfma_f32_16x16x32_bf16 v[76:79], v[128:131], v[226:229], v[76:79]
	v_mfma_f32_16x16x32_bf16 v[72:75], v[146:149], v[226:229], v[72:75]
	v_mfma_f32_16x16x32_bf16 v[124:127], v[132:135], v[206:209], v[124:127]
	v_mfma_f32_16x16x32_bf16 v[120:123], v[158:161], v[206:209], v[120:123]
	v_mfma_f32_16x16x32_bf16 v[108:111], v[132:135], v[214:217], v[108:111]
	v_mfma_f32_16x16x32_bf16 v[104:107], v[158:161], v[214:217], v[104:107]
	v_mfma_f32_16x16x32_bf16 v[92:95], v[132:135], v[222:225], v[92:95]
	v_mfma_f32_16x16x32_bf16 v[88:91], v[158:161], v[222:225], v[88:91]
	v_mfma_f32_16x16x32_bf16 v[76:79], v[132:135], v[230:233], v[76:79]
	v_mfma_f32_16x16x32_bf16 v[72:75], v[158:161], v[230:233], v[72:75]
	s_setprio 0
	s_setprio 1
	v_mfma_f32_16x16x32_bf16 v[116:119], v[168:171], v[202:205], v[116:119]
	v_mfma_f32_16x16x32_bf16 v[112:115], v[176:179], v[202:205], v[112:115]
	v_mfma_f32_16x16x32_bf16 v[100:103], v[168:171], v[210:213], v[100:103]
	v_mfma_f32_16x16x32_bf16 v[96:99], v[176:179], v[210:213], v[96:99]
	v_mfma_f32_16x16x32_bf16 v[84:87], v[168:171], v[218:221], v[84:87]
	v_mfma_f32_16x16x32_bf16 v[80:83], v[176:179], v[218:221], v[80:83]
	v_mfma_f32_16x16x32_bf16 v[68:71], v[168:171], v[226:229], v[68:71]
	v_mfma_f32_16x16x32_bf16 v[64:67], v[176:179], v[226:229], v[64:67]
	v_mfma_f32_16x16x32_bf16 v[116:119], v[172:175], v[206:209], v[116:119]
	v_mfma_f32_16x16x32_bf16 v[112:115], v[194:197], v[206:209], v[112:115]
	v_mfma_f32_16x16x32_bf16 v[100:103], v[172:175], v[214:217], v[100:103]
	v_mfma_f32_16x16x32_bf16 v[96:99], v[194:197], v[214:217], v[96:99]
	v_mfma_f32_16x16x32_bf16 v[84:87], v[172:175], v[222:225], v[84:87]
	v_mfma_f32_16x16x32_bf16 v[80:83], v[194:197], v[222:225], v[80:83]
	v_mfma_f32_16x16x32_bf16 v[68:71], v[172:175], v[230:233], v[68:71]
	v_mfma_f32_16x16x32_bf16 v[64:67], v[194:197], v[230:233], v[64:67]
	s_setprio 0
	s_barrier
	s_add_i32 s0, s14, s2
	v_lshl_add_u64 v[150:151], v[150:151], 0, s[36:37]
	s_mov_b32 m0, s0
	ds_read_b128 v[202:205], v167 offset:49152
	ds_read_b128 v[206:209], v167 offset:50176
	ds_read_b128 v[210:213], v167 offset:51200
	ds_read_b128 v[214:217], v167 offset:52224
	ds_read_b128 v[218:221], v167 offset:53248
	ds_read_b128 v[222:225], v167 offset:54272
	ds_read_b128 v[226:229], v167 offset:55296
	ds_read_b128 v[230:233], v167 offset:56320
	global_load_lds_dwordx4 v[150:151], off
	v_lshl_add_u64 v[150:151], v[162:163], 0, s[36:37]
	s_add_i32 m0, s0, 0x2000
	s_add_i32 s0, s15, s2
	global_load_lds_dwordx4 v[150:151], off
	v_lshl_add_u64 v[150:151], v[180:181], 0, s[36:37]
	s_mov_b32 m0, s0
	s_nop 0
	global_load_lds_dwordx4 v[150:151], off
	v_lshl_add_u64 v[150:151], v[234:235], 0, s[36:37]
	s_add_i32 m0, s0, 0x2000
	s_nop 0
	global_load_lds_dwordx4 v[150:151], off
	v_lshl_add_u64 v[150:151], v[236:237], 0, s[36:37]
	s_mov_b32 m0, s18
	s_nop 0
	global_load_lds_dwordx4 v[150:151], off
	v_lshl_add_u64 v[150:151], v[238:239], 0, s[36:37]
	s_mov_b32 m0, s28
	s_nop 0
	global_load_lds_dwordx4 v[150:151], off
	s_waitcnt vmcnt(8)
	s_waitcnt lgkmcnt(0)
	s_barrier
	s_setprio 1
	s_waitcnt lgkmcnt(0)
	v_mfma_f32_16x16x32_bf16 v[60:63], v[128:131], v[202:205], v[60:63]
	v_mfma_f32_16x16x32_bf16 v[56:59], v[146:149], v[202:205], v[56:59]
	v_mfma_f32_16x16x32_bf16 v[44:47], v[128:131], v[210:213], v[44:47]
	v_mfma_f32_16x16x32_bf16 v[40:43], v[146:149], v[210:213], v[40:43]
	v_mfma_f32_16x16x32_bf16 v[28:31], v[128:131], v[218:221], v[28:31]
	v_mfma_f32_16x16x32_bf16 v[24:27], v[146:149], v[218:221], v[24:27]
	v_mfma_f32_16x16x32_bf16 v[12:15], v[128:131], v[226:229], v[12:15]
	v_mfma_f32_16x16x32_bf16 v[8:11], v[146:149], v[226:229], v[8:11]
	v_mfma_f32_16x16x32_bf16 v[60:63], v[132:135], v[206:209], v[60:63]
	v_mfma_f32_16x16x32_bf16 v[56:59], v[158:161], v[206:209], v[56:59]
	v_mfma_f32_16x16x32_bf16 v[44:47], v[132:135], v[214:217], v[44:47]
	v_mfma_f32_16x16x32_bf16 v[40:43], v[158:161], v[214:217], v[40:43]
	v_mfma_f32_16x16x32_bf16 v[28:31], v[132:135], v[222:225], v[28:31]
	v_mfma_f32_16x16x32_bf16 v[24:27], v[158:161], v[222:225], v[24:27]
	v_mfma_f32_16x16x32_bf16 v[12:15], v[132:135], v[230:233], v[12:15]
	v_mfma_f32_16x16x32_bf16 v[8:11], v[158:161], v[230:233], v[8:11]
	s_setprio 0
	s_setprio 1
	v_mfma_f32_16x16x32_bf16 v[52:55], v[168:171], v[202:205], v[52:55]
	v_mfma_f32_16x16x32_bf16 v[48:51], v[176:179], v[202:205], v[48:51]
	v_mfma_f32_16x16x32_bf16 v[36:39], v[168:171], v[210:213], v[36:39]
	v_mfma_f32_16x16x32_bf16 v[32:35], v[176:179], v[210:213], v[32:35]
	v_mfma_f32_16x16x32_bf16 v[20:23], v[168:171], v[218:221], v[20:23]
	v_mfma_f32_16x16x32_bf16 v[16:19], v[176:179], v[218:221], v[16:19]
	v_mfma_f32_16x16x32_bf16 v[4:7], v[168:171], v[226:229], v[4:7]
	v_mfma_f32_16x16x32_bf16 v[0:3], v[176:179], v[226:229], v[0:3]
	v_mfma_f32_16x16x32_bf16 v[52:55], v[172:175], v[206:209], v[52:55]
	v_mfma_f32_16x16x32_bf16 v[48:51], v[194:197], v[206:209], v[48:51]
	v_mfma_f32_16x16x32_bf16 v[36:39], v[172:175], v[214:217], v[36:39]
	v_mfma_f32_16x16x32_bf16 v[32:35], v[194:197], v[214:217], v[32:35]
	v_mfma_f32_16x16x32_bf16 v[20:23], v[172:175], v[222:225], v[20:23]
	v_mfma_f32_16x16x32_bf16 v[16:19], v[194:197], v[222:225], v[16:19]
	v_mfma_f32_16x16x32_bf16 v[4:7], v[172:175], v[230:233], v[4:7]
	v_mfma_f32_16x16x32_bf16 v[0:3], v[194:197], v[230:233], v[0:3]
	s_setprio 0
	s_barrier
	s_add_u32 s42, s42, 0x100
	s_addc_u32 s43, s43, 0
	s_add_u32 s44, s44, 0x100
	s_addc_u32 s45, s45, 0
	s_cmp_ge_u32 s47, s31
	s_mov_b32 s0, s47
